# layer-0 weight conversion loops also issue all 32 loads of an item up front
# baseline (speedup 1.0000x reference)
.LBB0_702:
	v_lshl_add_u64 v[56:57], v[40:41], 0, s[6:7]
	global_load_dword v72, v[56:57], off nt
	v_lshl_add_u64 v[56:57], v[38:39], 0, s[6:7]
	global_load_dword v73, v[56:57], off nt
	v_lshl_add_u64 v[56:57], v[36:37], 0, s[6:7]
	global_load_dword v74, v[56:57], off nt
	v_lshl_add_u64 v[56:57], v[34:35], 0, s[6:7]
	global_load_dword v75, v[56:57], off nt
	v_lshl_add_u64 v[56:57], v[32:33], 0, s[6:7]
	global_load_dword v76, v[56:57], off nt
	v_lshl_add_u64 v[56:57], v[30:31], 0, s[6:7]
	global_load_dword v77, v[56:57], off nt
	v_lshl_add_u64 v[56:57], v[28:29], 0, s[6:7]
	global_load_dword v78, v[56:57], off nt
	v_lshl_add_u64 v[56:57], v[26:27], 0, s[6:7]
	global_load_dword v79, v[56:57], off nt
	s_add_u32 s6, s6, 0x10000
	s_addc_u32 s7, s7, 0
	v_lshl_add_u64 v[56:57], v[40:41], 0, s[6:7]
	global_load_dword v80, v[56:57], off nt
	v_lshl_add_u64 v[56:57], v[38:39], 0, s[6:7]
	global_load_dword v81, v[56:57], off nt
	v_lshl_add_u64 v[56:57], v[36:37], 0, s[6:7]
	global_load_dword v82, v[56:57], off nt
	v_lshl_add_u64 v[56:57], v[34:35], 0, s[6:7]
	global_load_dword v83, v[56:57], off nt
	v_lshl_add_u64 v[56:57], v[32:33], 0, s[6:7]
	global_load_dword v84, v[56:57], off nt
	v_lshl_add_u64 v[56:57], v[30:31], 0, s[6:7]
	global_load_dword v85, v[56:57], off nt
	v_lshl_add_u64 v[56:57], v[28:29], 0, s[6:7]
	global_load_dword v86, v[56:57], off nt
	v_lshl_add_u64 v[56:57], v[26:27], 0, s[6:7]
	global_load_dword v87, v[56:57], off nt
	s_add_u32 s6, s6, 0x10000
	s_addc_u32 s7, s7, 0
	v_lshl_add_u64 v[56:57], v[40:41], 0, s[6:7]
	global_load_dword v88, v[56:57], off nt
	v_lshl_add_u64 v[56:57], v[38:39], 0, s[6:7]
	global_load_dword v89, v[56:57], off nt
	v_lshl_add_u64 v[56:57], v[36:37], 0, s[6:7]
	global_load_dword v90, v[56:57], off nt
	v_lshl_add_u64 v[56:57], v[34:35], 0, s[6:7]
	global_load_dword v91, v[56:57], off nt
	v_lshl_add_u64 v[56:57], v[32:33], 0, s[6:7]
	global_load_dword v92, v[56:57], off nt
	v_lshl_add_u64 v[56:57], v[30:31], 0, s[6:7]
	global_load_dword v93, v[56:57], off nt
	v_lshl_add_u64 v[56:57], v[28:29], 0, s[6:7]
	global_load_dword v94, v[56:57], off nt
	v_lshl_add_u64 v[56:57], v[26:27], 0, s[6:7]
	global_load_dword v95, v[56:57], off nt
	s_add_u32 s6, s6, 0x10000
	s_addc_u32 s7, s7, 0
	v_lshl_add_u64 v[56:57], v[40:41], 0, s[6:7]
	global_load_dword v96, v[56:57], off nt
	v_lshl_add_u64 v[56:57], v[38:39], 0, s[6:7]
	global_load_dword v97, v[56:57], off nt
	v_lshl_add_u64 v[56:57], v[36:37], 0, s[6:7]
	global_load_dword v98, v[56:57], off nt
	v_lshl_add_u64 v[56:57], v[34:35], 0, s[6:7]
	global_load_dword v99, v[56:57], off nt
	v_lshl_add_u64 v[56:57], v[32:33], 0, s[6:7]
	global_load_dword v100, v[56:57], off nt
	v_lshl_add_u64 v[56:57], v[30:31], 0, s[6:7]
	global_load_dword v101, v[56:57], off nt
	v_lshl_add_u64 v[56:57], v[28:29], 0, s[6:7]
	global_load_dword v102, v[56:57], off nt
	v_lshl_add_u64 v[56:57], v[26:27], 0, s[6:7]
	global_load_dword v103, v[56:57], off nt
	s_add_u32 s6, s6, 0x10000
	s_addc_u32 s7, s7, 0
	v_add_u32_e32 v64, 0x400, v0
	s_waitcnt vmcnt(30)
	ds_write2_b32 v0, v72, v73 offset1:66
	s_waitcnt vmcnt(28)
	ds_write2_b32 v0, v74, v75 offset0:132 offset1:198
	s_waitcnt vmcnt(26)
	ds_write2_b32 v64, v76, v77 offset0:8 offset1:74
	s_waitcnt vmcnt(24)
	ds_write2_b32 v64, v78, v79 offset0:140 offset1:206
	v_add_u32_e32 v0, 0x840, v0
	v_add_u32_e32 v64, 0x400, v0
	s_waitcnt vmcnt(22)
	ds_write2_b32 v0, v80, v81 offset1:66
	s_waitcnt vmcnt(20)
	ds_write2_b32 v0, v82, v83 offset0:132 offset1:198
	s_waitcnt vmcnt(18)
	ds_write2_b32 v64, v84, v85 offset0:8 offset1:74
	s_waitcnt vmcnt(16)
	ds_write2_b32 v64, v86, v87 offset0:140 offset1:206
	v_add_u32_e32 v0, 0x840, v0
	v_add_u32_e32 v64, 0x400, v0
	s_waitcnt vmcnt(14)
	ds_write2_b32 v0, v88, v89 offset1:66
	s_waitcnt vmcnt(12)
	ds_write2_b32 v0, v90, v91 offset0:132 offset1:198
	s_waitcnt vmcnt(10)
	ds_write2_b32 v64, v92, v93 offset0:8 offset1:74
	s_waitcnt vmcnt(8)
	ds_write2_b32 v64, v94, v95 offset0:140 offset1:206
	v_add_u32_e32 v0, 0x840, v0
	v_add_u32_e32 v64, 0x400, v0
	s_waitcnt vmcnt(6)
	ds_write2_b32 v0, v96, v97 offset1:66
	s_waitcnt vmcnt(4)
	ds_write2_b32 v0, v98, v99 offset0:132 offset1:198
	s_waitcnt vmcnt(2)
	ds_write2_b32 v64, v100, v101 offset0:8 offset1:74
	s_waitcnt vmcnt(0)
	ds_write2_b32 v64, v102, v103 offset0:140 offset1:206
	v_add_u32_e32 v0, 0x840, v0
	s_waitcnt lgkmcnt(0)
	s_lshl_b32 s0, s17, 1
	ds_read2_b32 v[30:31], v44 offset0:33 offset1:41
	ds_read2_b32 v[32:33], v44 offset1:8
	ds_read2_b32 v[34:35], v44 offset0:66 offset1:74
	ds_read2_b32 v[36:37], v44 offset0:99 offset1:107
	ds_read2_b32 v[38:39], v44 offset0:132 offset1:140
	ds_read2_b32 v[40:41], v44 offset0:165 offset1:173
	ds_read2_b32 v[56:57], v44 offset0:198 offset1:206
	ds_read2_b32 v[58:59], v44 offset0:231 offset1:239
	s_add_i32 s0, s0, 0x1ae00
	s_and_b32 s0, s0, 0x1ffc0
	s_and_b32 s6, s9, 0x3e0
	s_lshl_b32 s0, s0, 1
	v_or_b32_e32 v0, s6, v43
	v_lshl_add_u64 v[60:61], v[2:3], 0, s[0:1]
	v_lshlrev_b32_e32 v0, 11, v0
	s_waitcnt lgkmcnt(6)
	v_cvt_pk_bf16_f32 v26, v32, v30
	s_waitcnt lgkmcnt(4)
	v_cvt_pk_bf16_f32 v27, v34, v36
	s_waitcnt lgkmcnt(2)
	v_cvt_pk_bf16_f32 v28, v38, v40
	s_waitcnt lgkmcnt(0)
	v_cvt_pk_bf16_f32 v29, v56, v58
	v_lshl_add_u64 v[62:63], v[60:61], 0, v[0:1]
	global_store_dwordx4 v[62:63], v[26:29], off
	v_or_b32_e32 v0, s6, v45
	v_lshlrev_b32_e32 v0, 11, v0
	v_cvt_pk_bf16_f32 v26, v33, v31
	v_cvt_pk_bf16_f32 v27, v35, v37
	v_cvt_pk_bf16_f32 v28, v39, v41
	v_cvt_pk_bf16_f32 v29, v57, v59
	ds_read2_b32 v[32:33], v44 offset0:49 offset1:57
	ds_read2_b32 v[34:35], v44 offset0:16 offset1:24
	ds_read2_b32 v[36:37], v44 offset0:82 offset1:90
	ds_read2_b32 v[38:39], v44 offset0:115 offset1:123
	ds_read2_b32 v[40:41], v44 offset0:148 offset1:156
	ds_read2_b32 v[56:57], v44 offset0:181 offset1:189
	ds_read2_b32 v[58:59], v44 offset0:214 offset1:222
	ds_read2_b32 v[62:63], v44 offset0:247 offset1:255
	v_lshl_add_u64 v[30:31], v[60:61], 0, v[0:1]
	v_or_b32_e32 v0, s6, v46
	v_lshlrev_b32_e32 v0, 11, v0
	global_store_dwordx4 v[30:31], v[26:29], off
	v_lshl_add_u64 v[30:31], v[60:61], 0, v[0:1]
	v_or_b32_e32 v0, s6, v47
	s_waitcnt lgkmcnt(6)
	v_cvt_pk_bf16_f32 v26, v34, v32
	s_waitcnt lgkmcnt(4)
	v_cvt_pk_bf16_f32 v27, v36, v38
	s_waitcnt lgkmcnt(2)
	v_cvt_pk_bf16_f32 v28, v40, v56
	s_waitcnt lgkmcnt(0)
	v_cvt_pk_bf16_f32 v29, v58, v62
	v_lshlrev_b32_e32 v0, 11, v0
	global_store_dwordx4 v[30:31], v[26:29], off
	v_lshl_add_u64 v[30:31], v[60:61], 0, v[0:1]
	s_mov_b64 s[6:7], 0
	v_cvt_pk_bf16_f32 v26, v35, v33
	v_cvt_pk_bf16_f32 v27, v37, v39
	v_cvt_pk_bf16_f32 v28, v41, v57
	v_cvt_pk_bf16_f32 v29, v59, v63
	global_store_dwordx4 v[30:31], v[26:29], off
	s_waitcnt lgkmcnt(0)

.LBB0_706:
	v_lshl_add_u64 v[56:57], v[40:41], 0, s[6:7]
	global_load_dword v72, v[56:57], off nt
	v_lshl_add_u64 v[56:57], v[38:39], 0, s[6:7]
	global_load_dword v73, v[56:57], off nt
	v_lshl_add_u64 v[56:57], v[36:37], 0, s[6:7]
	global_load_dword v74, v[56:57], off nt
	v_lshl_add_u64 v[56:57], v[34:35], 0, s[6:7]
	global_load_dword v75, v[56:57], off nt
	v_lshl_add_u64 v[56:57], v[32:33], 0, s[6:7]
	global_load_dword v76, v[56:57], off nt
	v_lshl_add_u64 v[56:57], v[30:31], 0, s[6:7]
	global_load_dword v77, v[56:57], off nt
	v_lshl_add_u64 v[56:57], v[28:29], 0, s[6:7]
	global_load_dword v78, v[56:57], off nt
	v_lshl_add_u64 v[56:57], v[26:27], 0, s[6:7]
	global_load_dword v79, v[56:57], off nt
	s_add_u32 s6, s6, 0x40000
	s_addc_u32 s7, s7, 0
	v_lshl_add_u64 v[56:57], v[40:41], 0, s[6:7]
	global_load_dword v80, v[56:57], off nt
	v_lshl_add_u64 v[56:57], v[38:39], 0, s[6:7]
	global_load_dword v81, v[56:57], off nt
	v_lshl_add_u64 v[56:57], v[36:37], 0, s[6:7]
	global_load_dword v82, v[56:57], off nt
	v_lshl_add_u64 v[56:57], v[34:35], 0, s[6:7]
	global_load_dword v83, v[56:57], off nt
	v_lshl_add_u64 v[56:57], v[32:33], 0, s[6:7]
	global_load_dword v84, v[56:57], off nt
	v_lshl_add_u64 v[56:57], v[30:31], 0, s[6:7]
	global_load_dword v85, v[56:57], off nt
	v_lshl_add_u64 v[56:57], v[28:29], 0, s[6:7]
	global_load_dword v86, v[56:57], off nt
	v_lshl_add_u64 v[56:57], v[26:27], 0, s[6:7]
	global_load_dword v87, v[56:57], off nt
	s_add_u32 s6, s6, 0x40000
	s_addc_u32 s7, s7, 0
	v_lshl_add_u64 v[56:57], v[40:41], 0, s[6:7]
	global_load_dword v88, v[56:57], off nt
	v_lshl_add_u64 v[56:57], v[38:39], 0, s[6:7]
	global_load_dword v89, v[56:57], off nt
	v_lshl_add_u64 v[56:57], v[36:37], 0, s[6:7]
	global_load_dword v90, v[56:57], off nt
	v_lshl_add_u64 v[56:57], v[34:35], 0, s[6:7]
	global_load_dword v91, v[56:57], off nt
	v_lshl_add_u64 v[56:57], v[32:33], 0, s[6:7]
	global_load_dword v92, v[56:57], off nt
	v_lshl_add_u64 v[56:57], v[30:31], 0, s[6:7]
	global_load_dword v93, v[56:57], off nt
	v_lshl_add_u64 v[56:57], v[28:29], 0, s[6:7]
	global_load_dword v94, v[56:57], off nt
	v_lshl_add_u64 v[56:57], v[26:27], 0, s[6:7]
	global_load_dword v95, v[56:57], off nt
	s_add_u32 s6, s6, 0x40000
	s_addc_u32 s7, s7, 0
	v_lshl_add_u64 v[56:57], v[40:41], 0, s[6:7]
	global_load_dword v96, v[56:57], off nt
	v_lshl_add_u64 v[56:57], v[38:39], 0, s[6:7]
	global_load_dword v97, v[56:57], off nt
	v_lshl_add_u64 v[56:57], v[36:37], 0, s[6:7]
	global_load_dword v98, v[56:57], off nt
	v_lshl_add_u64 v[56:57], v[34:35], 0, s[6:7]
	global_load_dword v99, v[56:57], off nt
	v_lshl_add_u64 v[56:57], v[32:33], 0, s[6:7]
	global_load_dword v100, v[56:57], off nt
	v_lshl_add_u64 v[56:57], v[30:31], 0, s[6:7]
	global_load_dword v101, v[56:57], off nt
	v_lshl_add_u64 v[56:57], v[28:29], 0, s[6:7]
	global_load_dword v102, v[56:57], off nt
	v_lshl_add_u64 v[56:57], v[26:27], 0, s[6:7]
	global_load_dword v103, v[56:57], off nt
	s_add_u32 s6, s6, 0x40000
	s_addc_u32 s7, s7, 0
	v_add_u32_e32 v64, 0x400, v0
	s_waitcnt vmcnt(30)
	ds_write2_b32 v0, v72, v73 offset1:66
	s_waitcnt vmcnt(28)
	ds_write2_b32 v0, v74, v75 offset0:132 offset1:198
	s_waitcnt vmcnt(26)
	ds_write2_b32 v64, v76, v77 offset0:8 offset1:74
	s_waitcnt vmcnt(24)
	ds_write2_b32 v64, v78, v79 offset0:140 offset1:206
	v_add_u32_e32 v0, 0x840, v0
	v_add_u32_e32 v64, 0x400, v0
	s_waitcnt vmcnt(22)
	ds_write2_b32 v0, v80, v81 offset1:66
	s_waitcnt vmcnt(20)
	ds_write2_b32 v0, v82, v83 offset0:132 offset1:198
	s_waitcnt vmcnt(18)
	ds_write2_b32 v64, v84, v85 offset0:8 offset1:74
	s_waitcnt vmcnt(16)
	ds_write2_b32 v64, v86, v87 offset0:140 offset1:206
	v_add_u32_e32 v0, 0x840, v0
	v_add_u32_e32 v64, 0x400, v0
	s_waitcnt vmcnt(14)
	ds_write2_b32 v0, v88, v89 offset1:66
	s_waitcnt vmcnt(12)
	ds_write2_b32 v0, v90, v91 offset0:132 offset1:198
	s_waitcnt vmcnt(10)
	ds_write2_b32 v64, v92, v93 offset0:8 offset1:74
	s_waitcnt vmcnt(8)
	ds_write2_b32 v64, v94, v95 offset0:140 offset1:206
	v_add_u32_e32 v0, 0x840, v0
	v_add_u32_e32 v64, 0x400, v0
	s_waitcnt vmcnt(6)
	ds_write2_b32 v0, v96, v97 offset1:66
	s_waitcnt vmcnt(4)
	ds_write2_b32 v0, v98, v99 offset0:132 offset1:198
	s_waitcnt vmcnt(2)
	ds_write2_b32 v64, v100, v101 offset0:8 offset1:74
	s_waitcnt vmcnt(0)
	ds_write2_b32 v64, v102, v103 offset0:140 offset1:206
	v_add_u32_e32 v0, 0x840, v0
	s_waitcnt lgkmcnt(0)
	ds_read2_b32 v[30:31], v44 offset0:33 offset1:41
	ds_read2_b32 v[32:33], v44 offset1:8
	ds_read2_b32 v[34:35], v44 offset0:66 offset1:74
	ds_read2_b32 v[36:37], v44 offset0:99 offset1:107
	ds_read2_b32 v[38:39], v44 offset0:132 offset1:140
	ds_read2_b32 v[40:41], v44 offset0:165 offset1:173
	ds_read2_b32 v[56:57], v44 offset0:198 offset1:206
	ds_read2_b32 v[58:59], v44 offset0:231 offset1:239
	s_add_i32 s0, s17, 0xdf00
	s_and_b32 s6, s9, 0xfe0
	s_and_b32 s0, s0, 0xff80
	v_or_b32_e32 v0, s6, v43
	v_lshl_add_u64 v[60:61], v[4:5], 0, s[0:1]
	v_lshlrev_b32_e32 v0, 11, v0
	s_waitcnt lgkmcnt(6)
	v_cvt_pk_bf16_f32 v26, v32, v30
	s_waitcnt lgkmcnt(4)
	v_cvt_pk_bf16_f32 v27, v34, v36
	s_waitcnt lgkmcnt(2)
	v_cvt_pk_bf16_f32 v28, v38, v40
	s_waitcnt lgkmcnt(0)
	v_cvt_pk_bf16_f32 v29, v56, v58
	v_lshl_add_u64 v[62:63], v[60:61], 0, v[0:1]
	global_store_dwordx4 v[62:63], v[26:29], off
	v_or_b32_e32 v0, s6, v45
	v_lshlrev_b32_e32 v0, 11, v0
	v_cvt_pk_bf16_f32 v26, v33, v31
	v_cvt_pk_bf16_f32 v27, v35, v37
	v_cvt_pk_bf16_f32 v28, v39, v41
	v_cvt_pk_bf16_f32 v29, v57, v59
	ds_read2_b32 v[32:33], v44 offset0:49 offset1:57
	ds_read2_b32 v[34:35], v44 offset0:16 offset1:24
	ds_read2_b32 v[36:37], v44 offset0:82 offset1:90
	ds_read2_b32 v[38:39], v44 offset0:115 offset1:123
	ds_read2_b32 v[40:41], v44 offset0:148 offset1:156
	ds_read2_b32 v[56:57], v44 offset0:181 offset1:189
	ds_read2_b32 v[58:59], v44 offset0:214 offset1:222
	ds_read2_b32 v[62:63], v44 offset0:247 offset1:255
	v_lshl_add_u64 v[30:31], v[60:61], 0, v[0:1]
	v_or_b32_e32 v0, s6, v46
	v_lshlrev_b32_e32 v0, 11, v0
	global_store_dwordx4 v[30:31], v[26:29], off
	v_lshl_add_u64 v[30:31], v[60:61], 0, v[0:1]
	v_or_b32_e32 v0, s6, v47
	s_waitcnt lgkmcnt(6)
	v_cvt_pk_bf16_f32 v26, v34, v32
	s_waitcnt lgkmcnt(4)
	v_cvt_pk_bf16_f32 v27, v36, v38
	s_waitcnt lgkmcnt(2)
	v_cvt_pk_bf16_f32 v28, v40, v56
	s_waitcnt lgkmcnt(0)
	v_cvt_pk_bf16_f32 v29, v58, v62
	v_lshlrev_b32_e32 v0, 11, v0
	global_store_dwordx4 v[30:31], v[26:29], off
	v_lshl_add_u64 v[30:31], v[60:61], 0, v[0:1]
	s_nop 0
	v_cvt_pk_bf16_f32 v26, v35, v33
	v_cvt_pk_bf16_f32 v27, v37, v39
	v_cvt_pk_bf16_f32 v28, v41, v57
	v_cvt_pk_bf16_f32 v29, v59, v63
	global_store_dwordx4 v[30:31], v[26:29], off
	s_waitcnt lgkmcnt(0)

.LBB0_711:
	v_lshl_add_u64 v[56:57], v[40:41], 0, s[6:7]
	global_load_dword v72, v[56:57], off nt
	v_lshl_add_u64 v[56:57], v[38:39], 0, s[6:7]
	global_load_dword v73, v[56:57], off nt
	v_lshl_add_u64 v[56:57], v[36:37], 0, s[6:7]
	global_load_dword v74, v[56:57], off nt
	v_lshl_add_u64 v[56:57], v[34:35], 0, s[6:7]
	global_load_dword v75, v[56:57], off nt
	v_lshl_add_u64 v[56:57], v[32:33], 0, s[6:7]
	global_load_dword v76, v[56:57], off nt
	v_lshl_add_u64 v[56:57], v[30:31], 0, s[6:7]
	global_load_dword v77, v[56:57], off nt
	v_lshl_add_u64 v[56:57], v[28:29], 0, s[6:7]
	global_load_dword v78, v[56:57], off nt
	v_lshl_add_u64 v[56:57], v[26:27], 0, s[6:7]
	global_load_dword v79, v[56:57], off nt
	s_add_u32 s6, s6, 0x10000
	s_addc_u32 s7, s7, 0
	v_lshl_add_u64 v[56:57], v[40:41], 0, s[6:7]
	global_load_dword v80, v[56:57], off nt
	v_lshl_add_u64 v[56:57], v[38:39], 0, s[6:7]
	global_load_dword v81, v[56:57], off nt
	v_lshl_add_u64 v[56:57], v[36:37], 0, s[6:7]
	global_load_dword v82, v[56:57], off nt
	v_lshl_add_u64 v[56:57], v[34:35], 0, s[6:7]
	global_load_dword v83, v[56:57], off nt
	v_lshl_add_u64 v[56:57], v[32:33], 0, s[6:7]
	global_load_dword v84, v[56:57], off nt
	v_lshl_add_u64 v[56:57], v[30:31], 0, s[6:7]
	global_load_dword v85, v[56:57], off nt
	v_lshl_add_u64 v[56:57], v[28:29], 0, s[6:7]
	global_load_dword v86, v[56:57], off nt
	v_lshl_add_u64 v[56:57], v[26:27], 0, s[6:7]
	global_load_dword v87, v[56:57], off nt
	s_add_u32 s6, s6, 0x10000
	s_addc_u32 s7, s7, 0
	v_lshl_add_u64 v[56:57], v[40:41], 0, s[6:7]
	global_load_dword v88, v[56:57], off nt
	v_lshl_add_u64 v[56:57], v[38:39], 0, s[6:7]
	global_load_dword v89, v[56:57], off nt
	v_lshl_add_u64 v[56:57], v[36:37], 0, s[6:7]
	global_load_dword v90, v[56:57], off nt
	v_lshl_add_u64 v[56:57], v[34:35], 0, s[6:7]
	global_load_dword v91, v[56:57], off nt
	v_lshl_add_u64 v[56:57], v[32:33], 0, s[6:7]
	global_load_dword v92, v[56:57], off nt
	v_lshl_add_u64 v[56:57], v[30:31], 0, s[6:7]
	global_load_dword v93, v[56:57], off nt
	v_lshl_add_u64 v[56:57], v[28:29], 0, s[6:7]
	global_load_dword v94, v[56:57], off nt
	v_lshl_add_u64 v[56:57], v[26:27], 0, s[6:7]
	global_load_dword v95, v[56:57], off nt
	s_add_u32 s6, s6, 0x10000
	s_addc_u32 s7, s7, 0
	v_lshl_add_u64 v[56:57], v[40:41], 0, s[6:7]
	global_load_dword v96, v[56:57], off nt
	v_lshl_add_u64 v[56:57], v[38:39], 0, s[6:7]
	global_load_dword v97, v[56:57], off nt
	v_lshl_add_u64 v[56:57], v[36:37], 0, s[6:7]
	global_load_dword v98, v[56:57], off nt
	v_lshl_add_u64 v[56:57], v[34:35], 0, s[6:7]
	global_load_dword v99, v[56:57], off nt
	v_lshl_add_u64 v[56:57], v[32:33], 0, s[6:7]
	global_load_dword v100, v[56:57], off nt
	v_lshl_add_u64 v[56:57], v[30:31], 0, s[6:7]
	global_load_dword v101, v[56:57], off nt
	v_lshl_add_u64 v[56:57], v[28:29], 0, s[6:7]
	global_load_dword v102, v[56:57], off nt
	v_lshl_add_u64 v[56:57], v[26:27], 0, s[6:7]
	global_load_dword v103, v[56:57], off nt
	s_add_u32 s6, s6, 0x10000
	s_addc_u32 s7, s7, 0
	v_add_u32_e32 v64, 0x400, v0
	s_waitcnt vmcnt(30)
	ds_write2_b32 v0, v72, v73 offset1:66
	s_waitcnt vmcnt(28)
	ds_write2_b32 v0, v74, v75 offset0:132 offset1:198
	s_waitcnt vmcnt(26)
	ds_write2_b32 v64, v76, v77 offset0:8 offset1:74
	s_waitcnt vmcnt(24)
	ds_write2_b32 v64, v78, v79 offset0:140 offset1:206
	v_add_u32_e32 v0, 0x840, v0
	v_add_u32_e32 v64, 0x400, v0
	s_waitcnt vmcnt(22)
	ds_write2_b32 v0, v80, v81 offset1:66
	s_waitcnt vmcnt(20)
	ds_write2_b32 v0, v82, v83 offset0:132 offset1:198
	s_waitcnt vmcnt(18)
	ds_write2_b32 v64, v84, v85 offset0:8 offset1:74
	s_waitcnt vmcnt(16)
	ds_write2_b32 v64, v86, v87 offset0:140 offset1:206
	v_add_u32_e32 v0, 0x840, v0
	v_add_u32_e32 v64, 0x400, v0
	s_waitcnt vmcnt(14)
	ds_write2_b32 v0, v88, v89 offset1:66
	s_waitcnt vmcnt(12)
	ds_write2_b32 v0, v90, v91 offset0:132 offset1:198
	s_waitcnt vmcnt(10)
	ds_write2_b32 v64, v92, v93 offset0:8 offset1:74
	s_waitcnt vmcnt(8)
	ds_write2_b32 v64, v94, v95 offset0:140 offset1:206
	v_add_u32_e32 v0, 0x840, v0
	v_add_u32_e32 v64, 0x400, v0
	s_waitcnt vmcnt(6)
	ds_write2_b32 v0, v96, v97 offset1:66
	s_waitcnt vmcnt(4)
	ds_write2_b32 v0, v98, v99 offset0:132 offset1:198
	s_waitcnt vmcnt(2)
	ds_write2_b32 v64, v100, v101 offset0:8 offset1:74
	s_waitcnt vmcnt(0)
	ds_write2_b32 v64, v102, v103 offset0:140 offset1:206
	v_add_u32_e32 v0, 0x840, v0
	s_waitcnt lgkmcnt(0)
	s_lshl_b32 s0, s17, 1
	ds_read2_b32 v[30:31], v44 offset0:33 offset1:41
	ds_read2_b32 v[32:33], v44 offset1:8
	ds_read2_b32 v[34:35], v44 offset0:66 offset1:74
	ds_read2_b32 v[36:37], v44 offset0:99 offset1:107
	ds_read2_b32 v[38:39], v44 offset0:132 offset1:140
	ds_read2_b32 v[40:41], v44 offset0:165 offset1:173
	ds_read2_b32 v[56:57], v44 offset0:198 offset1:206
	ds_read2_b32 v[58:59], v44 offset0:231 offset1:239
	s_add_i32 s0, s0, 0x1c900
	s_lshl_b32 s6, s17, 5
	s_and_b32 s0, s0, 0x1ffc0
	s_and_b32 s6, s6, 0x3e0
	s_lshl_b32 s0, s0, 1
	v_or_b32_e32 v0, s6, v43
	v_lshl_add_u64 v[60:61], v[6:7], 0, s[0:1]
	v_mul_u32_u24_e32 v0, 0xb00, v0
	s_waitcnt lgkmcnt(6)
	v_cvt_pk_bf16_f32 v26, v32, v30
	s_waitcnt lgkmcnt(4)
	v_cvt_pk_bf16_f32 v27, v34, v36
	s_waitcnt lgkmcnt(2)
	v_cvt_pk_bf16_f32 v28, v38, v40
	s_waitcnt lgkmcnt(0)
	v_cvt_pk_bf16_f32 v29, v56, v58
	v_lshl_add_u64 v[62:63], v[0:1], 1, v[60:61]
	global_store_dwordx4 v[62:63], v[26:29], off
	v_or_b32_e32 v0, s6, v45
	v_mul_u32_u24_e32 v0, 0xb00, v0
	v_cvt_pk_bf16_f32 v26, v33, v31
	v_cvt_pk_bf16_f32 v27, v35, v37
	v_cvt_pk_bf16_f32 v28, v39, v41
	v_cvt_pk_bf16_f32 v29, v57, v59
	ds_read2_b32 v[32:33], v44 offset0:16 offset1:24
	ds_read2_b32 v[34:35], v44 offset0:49 offset1:57
	ds_read2_b32 v[36:37], v44 offset0:82 offset1:90
	ds_read2_b32 v[38:39], v44 offset0:115 offset1:123
	ds_read2_b32 v[40:41], v44 offset0:148 offset1:156
	ds_read2_b32 v[56:57], v44 offset0:181 offset1:189
	ds_read2_b32 v[58:59], v44 offset0:214 offset1:222
	ds_read2_b32 v[62:63], v44 offset0:247 offset1:255
	v_lshl_add_u64 v[30:31], v[0:1], 1, v[60:61]
	v_or_b32_e32 v0, s6, v46
	v_mul_u32_u24_e32 v0, 0xb00, v0
	global_store_dwordx4 v[30:31], v[26:29], off
	v_lshl_add_u64 v[30:31], v[0:1], 1, v[60:61]
	v_or_b32_e32 v0, s6, v47
	s_waitcnt lgkmcnt(6)
	v_cvt_pk_bf16_f32 v26, v32, v34
	s_waitcnt lgkmcnt(4)
	v_cvt_pk_bf16_f32 v27, v36, v38
	s_waitcnt lgkmcnt(2)
	v_cvt_pk_bf16_f32 v28, v40, v56
	s_waitcnt lgkmcnt(0)
	v_cvt_pk_bf16_f32 v29, v58, v62
	v_mul_u32_u24_e32 v0, 0xb00, v0
	global_store_dwordx4 v[30:31], v[26:29], off
	v_lshl_add_u64 v[30:31], v[0:1], 1, v[60:61]
	s_nop 0
	v_cvt_pk_bf16_f32 v26, v33, v35
	v_cvt_pk_bf16_f32 v27, v37, v39
	v_cvt_pk_bf16_f32 v28, v41, v57
	v_cvt_pk_bf16_f32 v29, v59, v63
	global_store_dwordx4 v[30:31], v[26:29], off
	s_waitcnt lgkmcnt(0)

.LBB0_716:
	v_lshl_add_u64 v[56:57], v[40:41], 0, s[6:7]
	global_load_dword v72, v[56:57], off nt
	v_lshl_add_u64 v[56:57], v[38:39], 0, s[6:7]
	global_load_dword v73, v[56:57], off nt
	v_lshl_add_u64 v[56:57], v[36:37], 0, s[6:7]
	global_load_dword v74, v[56:57], off nt
	v_lshl_add_u64 v[56:57], v[34:35], 0, s[6:7]
	global_load_dword v75, v[56:57], off nt
	v_lshl_add_u64 v[56:57], v[32:33], 0, s[6:7]
	global_load_dword v76, v[56:57], off nt
	v_lshl_add_u64 v[56:57], v[30:31], 0, s[6:7]
	global_load_dword v77, v[56:57], off nt
	v_lshl_add_u64 v[56:57], v[28:29], 0, s[6:7]
	global_load_dword v78, v[56:57], off nt
	v_lshl_add_u64 v[56:57], v[26:27], 0, s[6:7]
	global_load_dword v79, v[56:57], off nt
	s_add_u32 s6, s6, 0x10000
	s_addc_u32 s7, s7, 0
	v_lshl_add_u64 v[56:57], v[40:41], 0, s[6:7]
	global_load_dword v80, v[56:57], off nt
	v_lshl_add_u64 v[56:57], v[38:39], 0, s[6:7]
	global_load_dword v81, v[56:57], off nt
	v_lshl_add_u64 v[56:57], v[36:37], 0, s[6:7]
	global_load_dword v82, v[56:57], off nt
	v_lshl_add_u64 v[56:57], v[34:35], 0, s[6:7]
	global_load_dword v83, v[56:57], off nt
	v_lshl_add_u64 v[56:57], v[32:33], 0, s[6:7]
	global_load_dword v84, v[56:57], off nt
	v_lshl_add_u64 v[56:57], v[30:31], 0, s[6:7]
	global_load_dword v85, v[56:57], off nt
	v_lshl_add_u64 v[56:57], v[28:29], 0, s[6:7]
	global_load_dword v86, v[56:57], off nt
	v_lshl_add_u64 v[56:57], v[26:27], 0, s[6:7]
	global_load_dword v87, v[56:57], off nt
	s_add_u32 s6, s6, 0x10000
	s_addc_u32 s7, s7, 0
	v_lshl_add_u64 v[56:57], v[40:41], 0, s[6:7]
	global_load_dword v88, v[56:57], off nt
	v_lshl_add_u64 v[56:57], v[38:39], 0, s[6:7]
	global_load_dword v89, v[56:57], off nt
	v_lshl_add_u64 v[56:57], v[36:37], 0, s[6:7]
	global_load_dword v90, v[56:57], off nt
	v_lshl_add_u64 v[56:57], v[34:35], 0, s[6:7]
	global_load_dword v91, v[56:57], off nt
	v_lshl_add_u64 v[56:57], v[32:33], 0, s[6:7]
	global_load_dword v92, v[56:57], off nt
	v_lshl_add_u64 v[56:57], v[30:31], 0, s[6:7]
	global_load_dword v93, v[56:57], off nt
	v_lshl_add_u64 v[56:57], v[28:29], 0, s[6:7]
	global_load_dword v94, v[56:57], off nt
	v_lshl_add_u64 v[56:57], v[26:27], 0, s[6:7]
	global_load_dword v95, v[56:57], off nt
	s_add_u32 s6, s6, 0x10000
	s_addc_u32 s7, s7, 0
	v_lshl_add_u64 v[56:57], v[40:41], 0, s[6:7]
	global_load_dword v96, v[56:57], off nt
	v_lshl_add_u64 v[56:57], v[38:39], 0, s[6:7]
	global_load_dword v97, v[56:57], off nt
	v_lshl_add_u64 v[56:57], v[36:37], 0, s[6:7]
	global_load_dword v98, v[56:57], off nt
	v_lshl_add_u64 v[56:57], v[34:35], 0, s[6:7]
	global_load_dword v99, v[56:57], off nt
	v_lshl_add_u64 v[56:57], v[32:33], 0, s[6:7]
	global_load_dword v100, v[56:57], off nt
	v_lshl_add_u64 v[56:57], v[30:31], 0, s[6:7]
	global_load_dword v101, v[56:57], off nt
	v_lshl_add_u64 v[56:57], v[28:29], 0, s[6:7]
	global_load_dword v102, v[56:57], off nt
	v_lshl_add_u64 v[56:57], v[26:27], 0, s[6:7]
	global_load_dword v103, v[56:57], off nt
	s_add_u32 s6, s6, 0x10000
	s_addc_u32 s7, s7, 0
	v_add_u32_e32 v64, 0x400, v0
	s_waitcnt vmcnt(30)
	ds_write2_b32 v0, v72, v73 offset1:66
	s_waitcnt vmcnt(28)
	ds_write2_b32 v0, v74, v75 offset0:132 offset1:198
	s_waitcnt vmcnt(26)
	ds_write2_b32 v64, v76, v77 offset0:8 offset1:74
	s_waitcnt vmcnt(24)
	ds_write2_b32 v64, v78, v79 offset0:140 offset1:206
	v_add_u32_e32 v0, 0x840, v0
	v_add_u32_e32 v64, 0x400, v0
	s_waitcnt vmcnt(22)
	ds_write2_b32 v0, v80, v81 offset1:66
	s_waitcnt vmcnt(20)
	ds_write2_b32 v0, v82, v83 offset0:132 offset1:198
	s_waitcnt vmcnt(18)
	ds_write2_b32 v64, v84, v85 offset0:8 offset1:74
	s_waitcnt vmcnt(16)
	ds_write2_b32 v64, v86, v87 offset0:140 offset1:206
	v_add_u32_e32 v0, 0x840, v0
	v_add_u32_e32 v64, 0x400, v0
	s_waitcnt vmcnt(14)
	ds_write2_b32 v0, v88, v89 offset1:66
	s_waitcnt vmcnt(12)
	ds_write2_b32 v0, v90, v91 offset0:132 offset1:198
	s_waitcnt vmcnt(10)
	ds_write2_b32 v64, v92, v93 offset0:8 offset1:74
	s_waitcnt vmcnt(8)
	ds_write2_b32 v64, v94, v95 offset0:140 offset1:206
	v_add_u32_e32 v0, 0x840, v0
	v_add_u32_e32 v64, 0x400, v0
	s_waitcnt vmcnt(6)
	ds_write2_b32 v0, v96, v97 offset1:66
	s_waitcnt vmcnt(4)
	ds_write2_b32 v0, v98, v99 offset0:132 offset1:198
	s_waitcnt vmcnt(2)
	ds_write2_b32 v64, v100, v101 offset0:8 offset1:74
	s_waitcnt vmcnt(0)
	ds_write2_b32 v64, v102, v103 offset0:140 offset1:206
	v_add_u32_e32 v0, 0x840, v0
	s_waitcnt lgkmcnt(0)
	s_lshl_b32 s0, s17, 1
	ds_read2_b32 v[30:31], v44 offset0:33 offset1:41
	ds_read2_b32 v[32:33], v44 offset1:8
	ds_read2_b32 v[34:35], v44 offset0:66 offset1:74
	ds_read2_b32 v[36:37], v44 offset0:99 offset1:107
	ds_read2_b32 v[38:39], v44 offset0:132 offset1:140
	ds_read2_b32 v[40:41], v44 offset0:165 offset1:173
	ds_read2_b32 v[56:57], v44 offset0:198 offset1:206
	ds_read2_b32 v[58:59], v44 offset0:231 offset1:239
	s_add_i32 s0, s0, 0x1d400
	s_lshl_b32 s6, s17, 5
	s_and_b32 s0, s0, 0x1ffc0
	s_and_b32 s6, s6, 0x3e0
	s_lshl_b32 s0, s0, 1
	v_or_b32_e32 v0, s6, v43
	v_lshl_add_u64 v[60:61], v[8:9], 0, s[0:1]
	v_mul_u32_u24_e32 v0, 0xb00, v0
	s_waitcnt lgkmcnt(6)
	v_cvt_pk_bf16_f32 v26, v32, v30
	s_waitcnt lgkmcnt(4)
	v_cvt_pk_bf16_f32 v27, v34, v36
	s_waitcnt lgkmcnt(2)
	v_cvt_pk_bf16_f32 v28, v38, v40
	s_waitcnt lgkmcnt(0)
	v_cvt_pk_bf16_f32 v29, v56, v58
	v_lshl_add_u64 v[62:63], v[0:1], 1, v[60:61]
	global_store_dwordx4 v[62:63], v[26:29], off
	v_or_b32_e32 v0, s6, v45
	v_mul_u32_u24_e32 v0, 0xb00, v0
	v_cvt_pk_bf16_f32 v26, v33, v31
	v_cvt_pk_bf16_f32 v27, v35, v37
	v_cvt_pk_bf16_f32 v28, v39, v41
	v_cvt_pk_bf16_f32 v29, v57, v59
	ds_read2_b32 v[32:33], v44 offset0:16 offset1:24
	ds_read2_b32 v[34:35], v44 offset0:49 offset1:57
	ds_read2_b32 v[36:37], v44 offset0:82 offset1:90
	ds_read2_b32 v[38:39], v44 offset0:115 offset1:123
	ds_read2_b32 v[40:41], v44 offset0:148 offset1:156
	ds_read2_b32 v[56:57], v44 offset0:181 offset1:189
	ds_read2_b32 v[58:59], v44 offset0:214 offset1:222
	ds_read2_b32 v[62:63], v44 offset0:247 offset1:255
	v_lshl_add_u64 v[30:31], v[0:1], 1, v[60:61]
	v_or_b32_e32 v0, s6, v46
	v_mul_u32_u24_e32 v0, 0xb00, v0
	global_store_dwordx4 v[30:31], v[26:29], off
	v_lshl_add_u64 v[30:31], v[0:1], 1, v[60:61]
	v_or_b32_e32 v0, s6, v47
	s_waitcnt lgkmcnt(6)
	v_cvt_pk_bf16_f32 v26, v32, v34
	s_waitcnt lgkmcnt(4)
	v_cvt_pk_bf16_f32 v27, v36, v38
	s_waitcnt lgkmcnt(2)
	v_cvt_pk_bf16_f32 v28, v40, v56
	s_waitcnt lgkmcnt(0)
	v_cvt_pk_bf16_f32 v29, v58, v62
	v_mul_u32_u24_e32 v0, 0xb00, v0
	global_store_dwordx4 v[30:31], v[26:29], off
	v_lshl_add_u64 v[30:31], v[0:1], 1, v[60:61]
	s_nop 0
	v_cvt_pk_bf16_f32 v26, v33, v35
	v_cvt_pk_bf16_f32 v27, v37, v39
	v_cvt_pk_bf16_f32 v28, v41, v57
	v_cvt_pk_bf16_f32 v29, v59, v63
	global_store_dwordx4 v[30:31], v[26:29], off
	s_waitcnt lgkmcnt(0)

.LBB0_721:
	v_lshl_add_u64 v[56:57], v[40:41], 0, s[6:7]
	global_load_dword v72, v[56:57], off nt
	v_lshl_add_u64 v[56:57], v[38:39], 0, s[6:7]
	global_load_dword v73, v[56:57], off nt
	v_lshl_add_u64 v[56:57], v[36:37], 0, s[6:7]
	global_load_dword v74, v[56:57], off nt
	v_lshl_add_u64 v[56:57], v[34:35], 0, s[6:7]
	global_load_dword v75, v[56:57], off nt
	v_lshl_add_u64 v[56:57], v[32:33], 0, s[6:7]
	global_load_dword v76, v[56:57], off nt
	v_lshl_add_u64 v[56:57], v[30:31], 0, s[6:7]
	global_load_dword v77, v[56:57], off nt
	v_lshl_add_u64 v[56:57], v[28:29], 0, s[6:7]
	global_load_dword v78, v[56:57], off nt
	v_lshl_add_u64 v[56:57], v[26:27], 0, s[6:7]
	global_load_dword v79, v[56:57], off nt
	s_add_u32 s6, s6, 0x58000
	s_addc_u32 s7, s7, 0
	v_lshl_add_u64 v[56:57], v[40:41], 0, s[6:7]
	global_load_dword v80, v[56:57], off nt
	v_lshl_add_u64 v[56:57], v[38:39], 0, s[6:7]
	global_load_dword v81, v[56:57], off nt
	v_lshl_add_u64 v[56:57], v[36:37], 0, s[6:7]
	global_load_dword v82, v[56:57], off nt
	v_lshl_add_u64 v[56:57], v[34:35], 0, s[6:7]
	global_load_dword v83, v[56:57], off nt
	v_lshl_add_u64 v[56:57], v[32:33], 0, s[6:7]
	global_load_dword v84, v[56:57], off nt
	v_lshl_add_u64 v[56:57], v[30:31], 0, s[6:7]
	global_load_dword v85, v[56:57], off nt
	v_lshl_add_u64 v[56:57], v[28:29], 0, s[6:7]
	global_load_dword v86, v[56:57], off nt
	v_lshl_add_u64 v[56:57], v[26:27], 0, s[6:7]
	global_load_dword v87, v[56:57], off nt
	s_add_u32 s6, s6, 0x58000
	s_addc_u32 s7, s7, 0
	v_lshl_add_u64 v[56:57], v[40:41], 0, s[6:7]
	global_load_dword v88, v[56:57], off nt
	v_lshl_add_u64 v[56:57], v[38:39], 0, s[6:7]
	global_load_dword v89, v[56:57], off nt
	v_lshl_add_u64 v[56:57], v[36:37], 0, s[6:7]
	global_load_dword v90, v[56:57], off nt
	v_lshl_add_u64 v[56:57], v[34:35], 0, s[6:7]
	global_load_dword v91, v[56:57], off nt
	v_lshl_add_u64 v[56:57], v[32:33], 0, s[6:7]
	global_load_dword v92, v[56:57], off nt
	v_lshl_add_u64 v[56:57], v[30:31], 0, s[6:7]
	global_load_dword v93, v[56:57], off nt
	v_lshl_add_u64 v[56:57], v[28:29], 0, s[6:7]
	global_load_dword v94, v[56:57], off nt
	v_lshl_add_u64 v[56:57], v[26:27], 0, s[6:7]
	global_load_dword v95, v[56:57], off nt
	s_add_u32 s6, s6, 0x58000
	s_addc_u32 s7, s7, 0
	v_lshl_add_u64 v[56:57], v[40:41], 0, s[6:7]
	global_load_dword v96, v[56:57], off nt
	v_lshl_add_u64 v[56:57], v[38:39], 0, s[6:7]
	global_load_dword v97, v[56:57], off nt
	v_lshl_add_u64 v[56:57], v[36:37], 0, s[6:7]
	global_load_dword v98, v[56:57], off nt
	v_lshl_add_u64 v[56:57], v[34:35], 0, s[6:7]
	global_load_dword v99, v[56:57], off nt
	v_lshl_add_u64 v[56:57], v[32:33], 0, s[6:7]
	global_load_dword v100, v[56:57], off nt
	v_lshl_add_u64 v[56:57], v[30:31], 0, s[6:7]
	global_load_dword v101, v[56:57], off nt
	v_lshl_add_u64 v[56:57], v[28:29], 0, s[6:7]
	global_load_dword v102, v[56:57], off nt
	v_lshl_add_u64 v[56:57], v[26:27], 0, s[6:7]
	global_load_dword v103, v[56:57], off nt
	s_add_u32 s6, s6, 0x58000
	s_addc_u32 s7, s7, 0
	v_add_u32_e32 v64, 0x400, v0
	s_waitcnt vmcnt(30)
	ds_write2_b32 v0, v72, v73 offset1:66
	s_waitcnt vmcnt(28)
	ds_write2_b32 v0, v74, v75 offset0:132 offset1:198
	s_waitcnt vmcnt(26)
	ds_write2_b32 v64, v76, v77 offset0:8 offset1:74
	s_waitcnt vmcnt(24)
	ds_write2_b32 v64, v78, v79 offset0:140 offset1:206
	v_add_u32_e32 v0, 0x840, v0
	v_add_u32_e32 v64, 0x400, v0
	s_waitcnt vmcnt(22)
	ds_write2_b32 v0, v80, v81 offset1:66
	s_waitcnt vmcnt(20)
	ds_write2_b32 v0, v82, v83 offset0:132 offset1:198
	s_waitcnt vmcnt(18)
	ds_write2_b32 v64, v84, v85 offset0:8 offset1:74
	s_waitcnt vmcnt(16)
	ds_write2_b32 v64, v86, v87 offset0:140 offset1:206
	v_add_u32_e32 v0, 0x840, v0
	v_add_u32_e32 v64, 0x400, v0
	s_waitcnt vmcnt(14)
	ds_write2_b32 v0, v88, v89 offset1:66
	s_waitcnt vmcnt(12)
	ds_write2_b32 v0, v90, v91 offset0:132 offset1:198
	s_waitcnt vmcnt(10)
	ds_write2_b32 v64, v92, v93 offset0:8 offset1:74
	s_waitcnt vmcnt(8)
	ds_write2_b32 v64, v94, v95 offset0:140 offset1:206
	v_add_u32_e32 v0, 0x840, v0
	v_add_u32_e32 v64, 0x400, v0
	s_waitcnt vmcnt(6)
	ds_write2_b32 v0, v96, v97 offset1:66
	s_waitcnt vmcnt(4)
	ds_write2_b32 v0, v98, v99 offset0:132 offset1:198
	s_waitcnt vmcnt(2)
	ds_write2_b32 v64, v100, v101 offset0:8 offset1:74
	s_waitcnt vmcnt(0)
	ds_write2_b32 v64, v102, v103 offset0:140 offset1:206
	v_add_u32_e32 v0, 0x840, v0
	s_and_b32 s0, 0xffff, s10
	s_and_b32 s6, 0xffff, s9
	s_cmpk_gt_u32 s6, 0x57
	s_cselect_b32 s6, 0xfffff500, 0
	s_cselect_b32 s7, 0x80, 0
	s_add_i32 s6, s6, s0
	s_waitcnt lgkmcnt(0)
	s_lshl_b32 s6, s6, 1
	s_and_b32 s0, s0, 0x60
	s_and_b32 s6, s6, 0xffffff00
	s_or_b32 s0, s0, s7
	ds_read2_b32 v[30:31], v44 offset0:33 offset1:41
	ds_read2_b32 v[32:33], v44 offset1:8
	ds_read2_b32 v[34:35], v44 offset0:66 offset1:74
	ds_read2_b32 v[36:37], v44 offset0:99 offset1:107
	ds_read2_b32 v[38:39], v44 offset0:132 offset1:140
	ds_read2_b32 v[40:41], v44 offset0:165 offset1:173
	ds_read2_b32 v[56:57], v44 offset0:198 offset1:206
	ds_read2_b32 v[58:59], v44 offset0:231 offset1:239
	s_or_b32 s6, s0, s6
	s_and_b32 s0, 0xffff, s8
	v_or_b32_e32 v62, s6, v43
	s_lshl_b32 s0, s0, 1
	v_ashrrev_i32_e32 v63, 31, v62
	v_lshl_add_u64 v[60:61], v[10:11], 0, s[0:1]
	v_lshlrev_b64 v[62:63], 11, v[62:63]
	s_waitcnt lgkmcnt(6)
	v_cvt_pk_bf16_f32 v26, v32, v30
	s_waitcnt lgkmcnt(4)
	v_cvt_pk_bf16_f32 v27, v34, v36
	s_waitcnt lgkmcnt(2)
	v_cvt_pk_bf16_f32 v28, v38, v40
	s_waitcnt lgkmcnt(0)
	v_cvt_pk_bf16_f32 v29, v56, v58
	v_lshl_add_u64 v[62:63], v[60:61], 0, v[62:63]
	v_or_b32_e32 v30, s6, v45
	global_store_dwordx4 v[62:63], v[26:29], off
	s_nop 1
	v_cvt_pk_bf16_f32 v26, v33, v31
	v_ashrrev_i32_e32 v31, 31, v30
	v_cvt_pk_bf16_f32 v27, v35, v37
	v_cvt_pk_bf16_f32 v28, v39, v41
	v_cvt_pk_bf16_f32 v29, v57, v59
	v_lshlrev_b64 v[30:31], 11, v[30:31]
	ds_read2_b32 v[32:33], v44 offset0:49 offset1:57
	ds_read2_b32 v[34:35], v44 offset0:16 offset1:24
	ds_read2_b32 v[36:37], v44 offset0:82 offset1:90
	ds_read2_b32 v[38:39], v44 offset0:115 offset1:123
	ds_read2_b32 v[40:41], v44 offset0:148 offset1:156
	ds_read2_b32 v[56:57], v44 offset0:181 offset1:189
	ds_read2_b32 v[58:59], v44 offset0:214 offset1:222
	ds_read2_b32 v[62:63], v44 offset0:247 offset1:255
	v_lshl_add_u64 v[30:31], v[60:61], 0, v[30:31]
	global_store_dwordx4 v[30:31], v[26:29], off
	v_or_b32_e32 v30, s6, v46
	v_ashrrev_i32_e32 v31, 31, v30
	v_lshlrev_b64 v[30:31], 11, v[30:31]
	s_waitcnt lgkmcnt(6)
	v_cvt_pk_bf16_f32 v26, v34, v32
	s_waitcnt lgkmcnt(4)
	v_cvt_pk_bf16_f32 v27, v36, v38
	s_waitcnt lgkmcnt(2)
	v_cvt_pk_bf16_f32 v28, v40, v56
	s_waitcnt lgkmcnt(0)
	v_cvt_pk_bf16_f32 v29, v58, v62
	v_lshl_add_u64 v[30:31], v[60:61], 0, v[30:31]
	global_store_dwordx4 v[30:31], v[26:29], off
	v_or_b32_e32 v30, s6, v47
	v_ashrrev_i32_e32 v31, 31, v30
	v_lshlrev_b64 v[30:31], 11, v[30:31]
	v_cvt_pk_bf16_f32 v26, v35, v33
	v_cvt_pk_bf16_f32 v27, v37, v39
	v_cvt_pk_bf16_f32 v28, v41, v57
	v_cvt_pk_bf16_f32 v29, v59, v63
	v_lshl_add_u64 v[30:31], v[60:61], 0, v[30:31]
	global_store_dwordx4 v[30:31], v[26:29], off
	s_waitcnt lgkmcnt(0)

.LBB0_726:
	v_lshl_add_u64 v[56:57], v[40:41], 0, s[10:11]
	global_load_dword v72, v[56:57], off nt
	v_lshl_add_u64 v[56:57], v[38:39], 0, s[10:11]
	global_load_dword v73, v[56:57], off nt
	v_lshl_add_u64 v[56:57], v[36:37], 0, s[10:11]
	global_load_dword v74, v[56:57], off nt
	v_lshl_add_u64 v[56:57], v[34:35], 0, s[10:11]
	global_load_dword v75, v[56:57], off nt
	v_lshl_add_u64 v[56:57], v[32:33], 0, s[10:11]
	global_load_dword v76, v[56:57], off nt
	v_lshl_add_u64 v[56:57], v[30:31], 0, s[10:11]
	global_load_dword v77, v[56:57], off nt
	v_lshl_add_u64 v[56:57], v[28:29], 0, s[10:11]
	global_load_dword v78, v[56:57], off nt
	v_lshl_add_u64 v[56:57], v[26:27], 0, s[10:11]
	global_load_dword v79, v[56:57], off nt
	s_add_u32 s10, s10, 0x58000
	s_addc_u32 s11, s11, 0
	v_lshl_add_u64 v[56:57], v[40:41], 0, s[10:11]
	global_load_dword v80, v[56:57], off nt
	v_lshl_add_u64 v[56:57], v[38:39], 0, s[10:11]
	global_load_dword v81, v[56:57], off nt
	v_lshl_add_u64 v[56:57], v[36:37], 0, s[10:11]
	global_load_dword v82, v[56:57], off nt
	v_lshl_add_u64 v[56:57], v[34:35], 0, s[10:11]
	global_load_dword v83, v[56:57], off nt
	v_lshl_add_u64 v[56:57], v[32:33], 0, s[10:11]
	global_load_dword v84, v[56:57], off nt
	v_lshl_add_u64 v[56:57], v[30:31], 0, s[10:11]
	global_load_dword v85, v[56:57], off nt
	v_lshl_add_u64 v[56:57], v[28:29], 0, s[10:11]
	global_load_dword v86, v[56:57], off nt
	v_lshl_add_u64 v[56:57], v[26:27], 0, s[10:11]
	global_load_dword v87, v[56:57], off nt
	s_add_u32 s10, s10, 0x58000
	s_addc_u32 s11, s11, 0
	v_lshl_add_u64 v[56:57], v[40:41], 0, s[10:11]
	global_load_dword v88, v[56:57], off nt
	v_lshl_add_u64 v[56:57], v[38:39], 0, s[10:11]
	global_load_dword v89, v[56:57], off nt
	v_lshl_add_u64 v[56:57], v[36:37], 0, s[10:11]
	global_load_dword v90, v[56:57], off nt
	v_lshl_add_u64 v[56:57], v[34:35], 0, s[10:11]
	global_load_dword v91, v[56:57], off nt
	v_lshl_add_u64 v[56:57], v[32:33], 0, s[10:11]
	global_load_dword v92, v[56:57], off nt
	v_lshl_add_u64 v[56:57], v[30:31], 0, s[10:11]
	global_load_dword v93, v[56:57], off nt
	v_lshl_add_u64 v[56:57], v[28:29], 0, s[10:11]
	global_load_dword v94, v[56:57], off nt
	v_lshl_add_u64 v[56:57], v[26:27], 0, s[10:11]
	global_load_dword v95, v[56:57], off nt
	s_add_u32 s10, s10, 0x58000
	s_addc_u32 s11, s11, 0
	v_lshl_add_u64 v[56:57], v[40:41], 0, s[10:11]
	global_load_dword v96, v[56:57], off nt
	v_lshl_add_u64 v[56:57], v[38:39], 0, s[10:11]
	global_load_dword v97, v[56:57], off nt
	v_lshl_add_u64 v[56:57], v[36:37], 0, s[10:11]
	global_load_dword v98, v[56:57], off nt
	v_lshl_add_u64 v[56:57], v[34:35], 0, s[10:11]
	global_load_dword v99, v[56:57], off nt
	v_lshl_add_u64 v[56:57], v[32:33], 0, s[10:11]
	global_load_dword v100, v[56:57], off nt
	v_lshl_add_u64 v[56:57], v[30:31], 0, s[10:11]
	global_load_dword v101, v[56:57], off nt
	v_lshl_add_u64 v[56:57], v[28:29], 0, s[10:11]
	global_load_dword v102, v[56:57], off nt
	v_lshl_add_u64 v[56:57], v[26:27], 0, s[10:11]
	global_load_dword v103, v[56:57], off nt
	s_add_u32 s10, s10, 0x58000
	s_addc_u32 s11, s11, 0
	v_add_u32_e32 v64, 0x400, v0
	s_waitcnt vmcnt(30)
	ds_write2_b32 v0, v72, v73 offset1:66
	s_waitcnt vmcnt(28)
	ds_write2_b32 v0, v74, v75 offset0:132 offset1:198
	s_waitcnt vmcnt(26)
	ds_write2_b32 v64, v76, v77 offset0:8 offset1:74
	s_waitcnt vmcnt(24)
	ds_write2_b32 v64, v78, v79 offset0:140 offset1:206
	v_add_u32_e32 v0, 0x840, v0
	v_add_u32_e32 v64, 0x400, v0
	s_waitcnt vmcnt(22)
	ds_write2_b32 v0, v80, v81 offset1:66
	s_waitcnt vmcnt(20)
	ds_write2_b32 v0, v82, v83 offset0:132 offset1:198
	s_waitcnt vmcnt(18)
	ds_write2_b32 v64, v84, v85 offset0:8 offset1:74
	s_waitcnt vmcnt(16)
	ds_write2_b32 v64, v86, v87 offset0:140 offset1:206
	v_add_u32_e32 v0, 0x840, v0
	v_add_u32_e32 v64, 0x400, v0
	s_waitcnt vmcnt(14)
	ds_write2_b32 v0, v88, v89 offset1:66
	s_waitcnt vmcnt(12)
	ds_write2_b32 v0, v90, v91 offset0:132 offset1:198
	s_waitcnt vmcnt(10)
	ds_write2_b32 v64, v92, v93 offset0:8 offset1:74
	s_waitcnt vmcnt(8)
	ds_write2_b32 v64, v94, v95 offset0:140 offset1:206
	v_add_u32_e32 v0, 0x840, v0
	v_add_u32_e32 v64, 0x400, v0
	s_waitcnt vmcnt(6)
	ds_write2_b32 v0, v96, v97 offset1:66
	s_waitcnt vmcnt(4)
	ds_write2_b32 v0, v98, v99 offset0:132 offset1:198
	s_waitcnt vmcnt(2)
	ds_write2_b32 v64, v100, v101 offset0:8 offset1:74
	s_waitcnt vmcnt(0)
	ds_write2_b32 v64, v102, v103 offset0:140 offset1:206
	v_add_u32_e32 v0, 0x840, v0
	s_cmpk_gt_i32 s0, 0x57
	s_cselect_b32 s0, 0xfffff500, 0
	s_cselect_b32 s7, 0x80, 0
	s_add_i32 s0, s0, s8
	s_waitcnt lgkmcnt(0)
	s_lshl_b32 s0, s0, 1
	s_and_b32 s8, s8, 0x60
	s_and_b32 s0, s0, 0xffffff00
	s_or_b32 s7, s8, s7
	ds_read2_b32 v[30:31], v44 offset0:33 offset1:41
	ds_read2_b32 v[32:33], v44 offset1:8
	ds_read2_b32 v[34:35], v44 offset0:66 offset1:74
	ds_read2_b32 v[36:37], v44 offset0:99 offset1:107
	ds_read2_b32 v[38:39], v44 offset0:132 offset1:140
	ds_read2_b32 v[40:41], v44 offset0:165 offset1:173
	ds_read2_b32 v[56:57], v44 offset0:198 offset1:206
	ds_read2_b32 v[58:59], v44 offset0:231 offset1:239
	s_or_b32 s0, s7, s0
	v_or_b32_e32 v62, s0, v43
	s_ashr_i32 s7, s6, 31
	v_ashrrev_i32_e32 v63, 31, v62
	v_lshl_add_u64 v[60:61], s[6:7], 1, v[12:13]
	v_lshlrev_b64 v[62:63], 11, v[62:63]
	s_waitcnt lgkmcnt(6)
	v_cvt_pk_bf16_f32 v26, v32, v30
	s_waitcnt lgkmcnt(4)
	v_cvt_pk_bf16_f32 v27, v34, v36
	s_waitcnt lgkmcnt(2)
	v_cvt_pk_bf16_f32 v28, v38, v40
	s_waitcnt lgkmcnt(0)
	v_cvt_pk_bf16_f32 v29, v56, v58
	v_lshl_add_u64 v[62:63], v[60:61], 0, v[62:63]
	v_or_b32_e32 v30, s0, v45
	global_store_dwordx4 v[62:63], v[26:29], off
	s_nop 1
	v_cvt_pk_bf16_f32 v26, v33, v31
	v_ashrrev_i32_e32 v31, 31, v30
	v_cvt_pk_bf16_f32 v27, v35, v37
	v_cvt_pk_bf16_f32 v28, v39, v41
	v_cvt_pk_bf16_f32 v29, v57, v59
	v_lshlrev_b64 v[30:31], 11, v[30:31]
	ds_read2_b32 v[32:33], v44 offset0:49 offset1:57
	ds_read2_b32 v[34:35], v44 offset0:16 offset1:24
	ds_read2_b32 v[36:37], v44 offset0:82 offset1:90
	ds_read2_b32 v[38:39], v44 offset0:115 offset1:123
	ds_read2_b32 v[40:41], v44 offset0:148 offset1:156
	ds_read2_b32 v[56:57], v44 offset0:181 offset1:189
	ds_read2_b32 v[58:59], v44 offset0:214 offset1:222
	ds_read2_b32 v[62:63], v44 offset0:247 offset1:255
	v_lshl_add_u64 v[30:31], v[60:61], 0, v[30:31]
	global_store_dwordx4 v[30:31], v[26:29], off
	v_or_b32_e32 v30, s0, v46
	v_ashrrev_i32_e32 v31, 31, v30
	v_lshlrev_b64 v[30:31], 11, v[30:31]
	s_waitcnt lgkmcnt(6)
	v_cvt_pk_bf16_f32 v26, v34, v32
	s_waitcnt lgkmcnt(4)
	v_cvt_pk_bf16_f32 v27, v36, v38
	s_waitcnt lgkmcnt(2)
	v_cvt_pk_bf16_f32 v28, v40, v56
	s_waitcnt lgkmcnt(0)
	v_cvt_pk_bf16_f32 v29, v58, v62
	v_lshl_add_u64 v[30:31], v[60:61], 0, v[30:31]
	global_store_dwordx4 v[30:31], v[26:29], off
	v_or_b32_e32 v30, s0, v47
	v_ashrrev_i32_e32 v31, 31, v30
	v_lshlrev_b64 v[30:31], 11, v[30:31]
	v_cvt_pk_bf16_f32 v26, v35, v33
	v_cvt_pk_bf16_f32 v27, v37, v39
	v_cvt_pk_bf16_f32 v28, v41, v57
	v_cvt_pk_bf16_f32 v29, v59, v63
	v_lshl_add_u64 v[30:31], v[60:61], 0, v[30:31]
	global_store_dwordx4 v[30:31], v[26:29], off
	s_waitcnt lgkmcnt(0)
	s_branch .LBB0_695
